# code alignment shift: +32 bytes of s_nop at kernel entry (moves every GEMM main loop by half an instruction-cache line)
# baseline (speedup 1.0000x reference)
_Z10fwd_kernel4Args:
	s_nop 0
	s_nop 0
	s_nop 0
	s_nop 0
	s_nop 0
	s_nop 0
	s_nop 0
	s_nop 0
	s_load_dwordx16 s[48:63], s[0:1], 0xc0
	s_load_dwordx2 s[96:97], s[0:1], 0x100
	s_load_dword s33, s[0:1], 0x108
	s_add_u32 s4, s0, 0x108
	s_addc_u32 s5, s1, 0
	v_and_b32_e32 v190, 0x3ff, v0
	v_writelane_b32 v254, s4, 0
	v_readfirstlane_b32 s3, v190
	v_cmp_eq_u32_e64 s[6:7], 0, v190
	v_writelane_b32 v254, s5, 1
	s_mov_b64 s[4:5], exec
	v_writelane_b32 v254, s6, 2
	s_nop 1
	v_writelane_b32 v254, s7, 3
	s_and_b64 s[6:7], s[4:5], s[6:7]
	s_mov_b64 exec, s[6:7]
	s_cbranch_execz .LBB0_2
	s_add_i32 s6, 0, 0x23fc0
	v_mov_b32_e32 v1, 0
	v_mov_b32_e32 v2, s6
	s_add_i32 s6, 0, 0x23fc4
	ds_write_b32 v2, v1
	v_mov_b32_e32 v2, s6
	ds_write_b32 v2, v1
